# ST state workspace regrouped so one k-slice of four rows is a full 128-byte line (gla_scan stores / gla_out loads touch 4x fewer lines)
# speedup vs baseline: 1.0079x; 1.0079x over previous
;     ...
;     for (int u = vb; u < 256; u += nb) {
;         const int b = u >> 5, hh = (u >> 3) & 3, ksl = u & 7;
;         const int kc0 = hh * 128 + ksl * 16 + 2 * w;
;         float wa[2][16], bb[2];
; #pragma unroll
;         for (int e = 0; e < 2; ++e) { bb[e] = ba[kc0 + e];
; #pragma unroll
;             for (int jj = 0; jj < 16; ++jj) wa[e][jj] = w2[jj * 512 + kc0 + e]; }
;         f32x4 acc[2];
; #pragma unroll
;         for (int e = 0; e < 2; ++e) acc[e] = (f32x4){0.f, 0.f, 0.f, 0.f};
;         __syncthreads();
;         f32x4 a4n[4]; unsigned krawn; bf16x8 vfrn[2][2];
;         auto ldchunk = [&](int n) {
;             const int tok = b * 4096 + n * 64 + l;
; #pragma unroll
;             for (int q = 0; q < 4; ++q) a4n[q] = *(const f32x4*)(GA + (size_t)tok * 16 + 4 * q);
;             krawn = *(const unsigned*)(GK + (size_t)tok * 512 + kc0);
; #pragma unroll
;             for (int e = 0; e < 2; ++e)
; #pragma unroll
;                 for (int ks = 0; ks < 2; ++ks)
;                     vfrn[e][ks] = *(const bf16x8*)(GVT + ((size_t)(b * 1024 + hh * 256 + (2 * w + e) * 16 + (l & 15))) * 4096 + n * 64 + ks * 32 + (l >> 4) * 8);
;         };
;         ldchunk(0);
;         for (int n = 0; n < 64; ++n) {
;             const int buf = n & 1;
;             f32x4 a4[4]; bf16x8 vfr[2][2];
; #pragma unroll
;             for (int q = 0; q < 4; ++q) a4[q] = a4n[q];
;             const unsigned kraw = krawn;
; #pragma unroll
;             for (int e = 0; e < 2; ++e)
; #pragma unroll
;                 for (int ks = 0; ks < 2; ++ks) vfr[e][ks] = vfrn[e][ks];
;             if (n + 1 < 64) ldchunk(n + 1);
.LBB0_418:
	s_bfe_u32 s57, s56, 0x20003
	s_lshl_b32 s21, s56, 4
	s_and_b32 s21, s21, 0x70
	s_lshl_b32 s20, s57, 7
	s_or_b32 s20, s20, s21
	s_ashr_i32 s28, s56, 5
	v_mov_b32_e32 v220, 0xbfb8aa3b
	v_mov_b32_e32 v222, 1.0
	v_mov_b32_e32 v223, 1.0
	v_mov_b32_e32 v224, 0x3f317217
	v_mov_b32_e32 v225, 0x3f317217
	v_mov_b32_e32 v226, 0x3377d1cf
	v_mov_b32_e32 v227, 0x3377d1cf
	v_mov_b32_e32 v228, 0x3fb8aa3b
	v_mov_b32_e32 v229, 0x3fb8aa3b
	v_mov_b32_e32 v214, 0x3d800000
	v_mov_b32_e32 v215, 0x3d800000
	v_lshrrev_b32_e32 v27, 6, v249
	v_lshrrev_b32_e32 v61, 3, v160
	v_lshl_add_u32 v60, v27, 3, v61
	v_and_b32_e32 v62, 7, v160
	v_lshlrev_b32_e32 v230, 3, v160
	v_lshl_add_u32 v230, v27, 9, v230
	v_lshlrev_b32_e32 v231, 2, v62
	v_lshl_add_u32 v231, v60, 10, v231
	v_mul_u32_u24_e32 v28, 0x50, v60
	v_lshl_add_u32 v28, v62, 3, v28
	v_add_u32_e32 v28, 0x2010, v28
	v_mul_u32_u24_e32 v29, 0x50, v160
	v_add_u32_e32 v29, 0x2010, v29
	v_mul_u32_u24_e32 v30, 0x104, v62
	v_lshl_add_u32 v30, v60, 2, v30
	v_add_u32_e32 v30, 0x5010, v30
	v_mul_u32_u24_e32 v31, 0x104, v27
	v_lshl_add_u32 v31, v160, 2, v31
	v_add_u32_e32 v31, 0x5010, v31
	v_lshrrev_b32_e32 v64, 4, v160
	v_lshlrev_b32_e32 v232, 13, v72
	v_lshl_add_u32 v232, v64, 4, v232
	v_add_u32_e32 v233, 0x20000, v232
	v_lshrrev_b32_e32 v66, 2, v72
	v_lshlrev_b32_e32 v234, 10, v66
	v_and_b32_e32 v66, 3, v72
	v_lshl_add_u32 v234, v66, 5, v234
	v_lshl_add_u32 v234, v64, 3, v234
	v_add_u32_e32 v235, 0x1000, v234
	v_add_u32_e32 v65, s20, v161
	v_lshlrev_b32_e32 v65, 2, v65
	s_mov_b64 s[50:51], s[8:9]
	global_load_dwordx2 v[86:87], v65, s[50:51]
	global_load_dwordx2 v[88:89], v65, s[50:51] offset:2048
	s_add_u32 s50, s50, 0x1000
	s_addc_u32 s51, s51, 0
	global_load_dwordx2 v[90:91], v65, s[50:51]
	global_load_dwordx2 v[92:93], v65, s[50:51] offset:2048
	s_add_u32 s50, s50, 0x1000
	s_addc_u32 s51, s51, 0
	global_load_dwordx2 v[94:95], v65, s[50:51]
	global_load_dwordx2 v[96:97], v65, s[50:51] offset:2048
	s_add_u32 s50, s50, 0x1000
	s_addc_u32 s51, s51, 0
	global_load_dwordx2 v[98:99], v65, s[50:51]
	global_load_dwordx2 v[100:101], v65, s[50:51] offset:2048
	s_add_u32 s50, s50, 0x1000
	s_addc_u32 s51, s51, 0
	global_load_dwordx2 v[102:103], v65, s[50:51]
	global_load_dwordx2 v[104:105], v65, s[50:51] offset:2048
	s_add_u32 s50, s50, 0x1000
	s_addc_u32 s51, s51, 0
	global_load_dwordx2 v[106:107], v65, s[50:51]
	global_load_dwordx2 v[108:109], v65, s[50:51] offset:2048
	s_add_u32 s50, s50, 0x1000
	s_addc_u32 s51, s51, 0
	global_load_dwordx2 v[110:111], v65, s[50:51]
	global_load_dwordx2 v[112:113], v65, s[50:51] offset:2048
	s_add_u32 s50, s50, 0x1000
	s_addc_u32 s51, s51, 0
	global_load_dwordx2 v[114:115], v65, s[50:51]
	global_load_dwordx2 v[116:117], v65, s[50:51] offset:2048
	s_add_u32 s50, s50, 0x1000
	s_addc_u32 s51, s51, 0
	global_load_dwordx2 v[118:119], v65, s[18:19]
	v_readlane_b32 s26, v253, 13
	v_readlane_b32 s27, v253, 14
	v_readlane_b32 s58, v254, 26
	v_readlane_b32 s59, v254, 27
	v_readlane_b32 s34, v253, 11
	v_readlane_b32 s35, v253, 12
	v_readlane_b32 s100, v254, 28
	v_readlane_b32 s101, v254, 29
	s_lshl_b32 s52, s28, 18
	s_add_u32 s26, s26, s52
	s_addc_u32 s27, s27, 0
	s_lshl_b32 s52, s28, 22
	s_lshl_b32 s53, s20, 1
	s_add_u32 s52, s52, s53
	s_add_u32 s58, s58, s52
	s_addc_u32 s59, s59, 0
	s_lshl_b32 s52, s28, 23
	s_lshl_b32 s53, s57, 21
	s_add_u32 s52, s52, s53
	s_add_u32 s34, s34, s52
	s_addc_u32 s35, s35, 0
	s_lshl_b32 s52, s28, 8
	s_or_b32 s52, s52, s57
	s_lshl_b32 s52, s52, 16
	s_lshl_b32 s53, s21, 3
	s_add_u32 s52, s52, s53
	s_add_u32 s100, s100, s52
	s_addc_u32 s101, s101, 0
	v_mov_b32_e32 v0, 0
	v_mov_b32_e32 v1, 0
	v_mov_b32_e32 v2, 0
	v_mov_b32_e32 v3, 0
	v_mov_b32_e32 v4, 0
	v_mov_b32_e32 v5, 0
	v_mov_b32_e32 v6, 0
	v_mov_b32_e32 v7, 0
	s_barrier
	v_lshlrev_b32_e32 v25, 8, v162
	s_mov_b32 s57, 0
	global_load_dwordx2 v[48:49], v230, s[26:27]
	global_load_dword v50, v231, s[58:59]
	s_add_u32 s26, s26, 0x1000
	s_addc_u32 s27, s27, 0
	s_add_u32 s58, s58, 0x10000
	s_addc_u32 s59, s59, 0
	global_load_dwordx2 v[52:53], v230, s[26:27]
	global_load_dword v54, v231, s[58:59]
	s_add_u32 s26, s26, 0x1000
	s_addc_u32 s27, s27, 0
	s_add_u32 s58, s58, 0x10000
	s_addc_u32 s59, s59, 0
	global_load_dwordx2 v[56:57], v230, s[26:27]
	global_load_dword v58, v231, s[58:59]
	s_add_u32 s26, s26, 0x1000
	s_addc_u32 s27, s27, 0
	s_add_u32 s58, s58, 0x10000
	s_addc_u32 s59, s59, 0
	v_xor_b32_e32 v26, s57, v25
	v_add_u32_e32 v59, v26, v232
	v_add_u32_e32 v63, 0x20000, v59
	global_load_dwordx4 v[32:35], v59, s[34:35]
	global_load_dwordx4 v[36:39], v59, s[34:35] offset:64
	global_load_dwordx4 v[40:43], v63, s[34:35]
	global_load_dwordx4 v[44:47], v63, s[34:35] offset:64
	s_add_u32 s57, s57, 0x80
	s_waitcnt vmcnt(0)
	ds_write_b64 v28, v[48:49] offset:0
	ds_write_b32 v30, v50 offset:0
	s_waitcnt lgkmcnt(0)
	s_barrier
; DI bf16_t f2bf(float x) { return (bf16_t)(pk2(x, 0.f) & 0xffffu); }
;     ...
;         for (int n = 0; n < 64; ++n) {
;             const int buf = n & 1;
;             f32x4 a4[4]; bf16x8 vfr[2][2];
; #pragma unroll
;             for (int q = 0; q < 4; ++q) a4[q] = a4n[q];
;             const unsigned kraw = krawn;
; #pragma unroll
;             for (int e = 0; e < 2; ++e)
; #pragma unroll
;                 for (int ks = 0; ks < 2; ++ks) vfr[e][ks] = vfrn[e][ks];
;             if (n + 1 < 64) ldchunk(n + 1);
;             float cum[2];
; #pragma unroll
;             for (int e = 0; e < 2; ++e) {
;                 float z = bb[e];
; #pragma unroll
;                 for (int q = 0; q < 4; ++q) { z += a4[q].x * wa[e][4 * q] + a4[q].y * wa[e][4 * q + 1] + a4[q].z * wa[e][4 * q + 2] + a4[q].w * wa[e][4 * q + 3]; }
;                 cum[e] = (fminf(z, 0.f) - __logf(1.f + __expf(-fabsf(z)))) * (1.f / 16.f);
;             }
; #pragma unroll
;             for (int o = 1; o < 64; o <<= 1) {
;                 const float t0 = __shfl_up(cum[0], o), t1 = __shfl_up(cum[1], o);
;                 if (l >= o) { cum[0] += t0; cum[1] += t1; }
;             }
;             const float tot0 = __shfl(cum[0], 63), tot1 = __shfl(cum[1], 63);
;             kdl[(buf * 16 + 2 * w) * 64 + l] = f2bf(bf2f(kraw & 0xffffu) * __expf(tot0 - cum[0]));
;             kdl[(buf * 16 + 2 * w + 1) * 64 + l] = f2bf(bf2f(kraw >> 16) * __expf(tot1 - cum[1]));
;             if (l == 0) { decl[buf * 16 + 2 * w] = __expf(tot0); decl[buf * 16 + 2 * w + 1] = __expf(tot1); }
;             __syncthreads();
;             const f32x4 d4 = *(const f32x4*)(decl + buf * 16 + (l >> 4) * 4);
; #pragma unroll
;             for (int e = 0; e < 2; ++e) acc[e] = acc[e] * d4;
; #pragma unroll
;             for (int ks = 0; ks < 2; ++ks) {
;                 const bf16x8 af = *(const bf16x8*)(kdl + (buf * 16 + (l & 15)) * 64 + ks * 32 + (l >> 4) * 8);
; #pragma unroll
;                 for (int e = 0; e < 2; ++e) acc[e] = MFMA16(af, vfr[e][ks], acc[e]);
;             }
;             const int cidx = b * 64 + n;
; #pragma unroll
;             for (int e = 0; e < 2; ++e) {
;                 const int vv = (2 * w + e) * 16 + (l & 15);
;                 *(u32x2*)(ST + (((size_t)(cidx * 4 + hh)) * 256 + vv) * 128 + ksl * 16 + (l >> 4) * 4) = pk4(acc[e].x, acc[e].y, acc[e].z, acc[e].w);
;             }
;         }
	ds_read_b128 v[8:11], v29 offset:0
	ds_read_b128 v[12:15], v29 offset:16
	ds_read_b128 v[16:19], v29 offset:32
	ds_read_b128 v[20:23], v29 offset:48
	ds_read_b32 v24, v31 offset:0
	global_load_dwordx2 v[48:49], v230, s[26:27]
	global_load_dword v50, v231, s[58:59]
	s_add_u32 s26, s26, 0x1000
	s_addc_u32 s27, s27, 0
	s_add_u32 s58, s58, 0x10000
	s_addc_u32 s59, s59, 0
	v_xor_b32_e32 v26, s57, v25
	v_add_u32_e32 v59, v26, v232
	v_add_u32_e32 v63, 0x20000, v59
	global_load_dwordx4 v[178:181], v59, s[34:35]
	global_load_dwordx4 v[182:185], v59, s[34:35] offset:64
	global_load_dwordx4 v[186:189], v63, s[34:35]
	global_load_dwordx4 v[190:193], v63, s[34:35] offset:64
	s_add_u32 s57, s57, 0x80
	s_waitcnt lgkmcnt(0)
	v_pk_fma_f32 v[64:65], v[8:9], v[86:87], v[118:119] op_sel:[0,0,0] op_sel_hi:[0,1,1]
	v_pk_mul_f32 v[66:67], v[16:17], v[102:103] op_sel:[0,0] op_sel_hi:[0,1]
	v_pk_fma_f32 v[64:65], v[8:9], v[88:89], v[64:65] op_sel:[1,0,0] op_sel_hi:[1,1,1]
	v_pk_fma_f32 v[66:67], v[16:17], v[104:105], v[66:67] op_sel:[1,0,0] op_sel_hi:[1,1,1]
	v_pk_fma_f32 v[64:65], v[10:11], v[90:91], v[64:65] op_sel:[0,0,0] op_sel_hi:[0,1,1]
	v_pk_fma_f32 v[66:67], v[18:19], v[106:107], v[66:67] op_sel:[0,0,0] op_sel_hi:[0,1,1]
	v_pk_fma_f32 v[64:65], v[10:11], v[92:93], v[64:65] op_sel:[1,0,0] op_sel_hi:[1,1,1]
	v_pk_fma_f32 v[66:67], v[18:19], v[108:109], v[66:67] op_sel:[1,0,0] op_sel_hi:[1,1,1]
	v_pk_fma_f32 v[64:65], v[12:13], v[94:95], v[64:65] op_sel:[0,0,0] op_sel_hi:[0,1,1]
	v_pk_fma_f32 v[66:67], v[20:21], v[110:111], v[66:67] op_sel:[0,0,0] op_sel_hi:[0,1,1]
	v_pk_fma_f32 v[64:65], v[12:13], v[96:97], v[64:65] op_sel:[1,0,0] op_sel_hi:[1,1,1]
	v_pk_fma_f32 v[66:67], v[20:21], v[112:113], v[66:67] op_sel:[1,0,0] op_sel_hi:[1,1,1]
	v_pk_fma_f32 v[64:65], v[14:15], v[98:99], v[64:65] op_sel:[0,0,0] op_sel_hi:[0,1,1]
	v_pk_fma_f32 v[66:67], v[22:23], v[114:115], v[66:67] op_sel:[0,0,0] op_sel_hi:[0,1,1]
	v_pk_fma_f32 v[64:65], v[14:15], v[100:101], v[64:65] op_sel:[1,0,0] op_sel_hi:[1,1,1]
	v_pk_fma_f32 v[66:67], v[22:23], v[116:117], v[66:67] op_sel:[1,0,0] op_sel_hi:[1,1,1]
	v_lshlrev_b32_e32 v148, 16, v24
	v_pk_add_f32 v[64:65], v[64:65], v[66:67]
	v_and_b32_e32 v149, 0xffff0000, v24
	v_mul_f32_e64 v68, |v64|, v220
	v_mul_f32_e64 v69, |v65|, v220
	v_exp_f32_e32 v68, v68
	v_exp_f32_e32 v69, v69
	v_min_f32_e32 v70, 0, v64
	v_min_f32_e32 v71, 0, v65
	v_pk_add_f32 v[68:69], v[68:69], v[222:223]
	s_nop 0
	v_log_f32_e32 v138, v68
	v_log_f32_e32 v139, v69
	s_nop 0
	v_pk_mul_f32 v[140:141], v[138:139], v[224:225]
	s_nop 0
	v_pk_fma_f32 v[142:143], v[138:139], v[224:225], v[140:141] neg_lo:[0,0,1] neg_hi:[0,0,1]
	s_nop 0
	v_pk_fma_f32 v[142:143], v[138:139], v[226:227], v[142:143]
	s_nop 0
	v_pk_fma_f32 v[142:143], v[138:139], v[224:225], v[142:143]
	s_nop 0
	v_pk_add_f32 v[144:145], v[70:71], v[142:143] neg_lo:[0,1] neg_hi:[0,1]
	s_nop 0
	v_pk_mul_f32 v[144:145], v[144:145], v[214:215]
	s_nop 1
	v_add_f32_dpp v144, v144, v144 row_shr:1 row_mask:0xf bank_mask:0xf
	v_add_f32_dpp v145, v145, v145 row_shr:1 row_mask:0xf bank_mask:0xf
	s_nop 0
	v_add_f32_dpp v144, v144, v144 row_shr:2 row_mask:0xf bank_mask:0xf
	v_add_f32_dpp v145, v145, v145 row_shr:2 row_mask:0xf bank_mask:0xf
	s_nop 0
	v_add_f32_dpp v144, v144, v144 row_shr:4 row_mask:0xf bank_mask:0xf
	v_add_f32_dpp v145, v145, v145 row_shr:4 row_mask:0xf bank_mask:0xf
	s_nop 0
	v_add_f32_dpp v144, v144, v144 row_shr:8 row_mask:0xf bank_mask:0xf
	v_add_f32_dpp v145, v145, v145 row_shr:8 row_mask:0xf bank_mask:0xf
	s_nop 0
	v_add_f32_dpp v144, v144, v144 row_bcast:15 row_mask:0xa bank_mask:0xf
	v_add_f32_dpp v145, v145, v145 row_bcast:15 row_mask:0xa bank_mask:0xf
	s_nop 0
	v_add_f32_dpp v144, v144, v144 row_bcast:31 row_mask:0xc bank_mask:0xf
	v_add_f32_dpp v145, v145, v145 row_bcast:31 row_mask:0xc bank_mask:0xf
	s_nop 0
	v_readlane_b32 s98, v144, 63
	v_readlane_b32 s99, v145, 63
	s_nop 1
	v_pk_add_f32 v[146:147], s[98:99], v[144:145] neg_lo:[0,1] neg_hi:[0,1]
	v_mul_f32_e64 v152, s98, v228
	v_mul_f32_e64 v153, s99, v228
	v_pk_mul_f32 v[146:147], v[146:147], v[228:229]
	v_exp_f32_e32 v152, v152
	v_exp_f32_e32 v153, v153
	v_exp_f32_e32 v146, v146
	v_exp_f32_e32 v147, v147
	s_nop 0
	v_pk_mul_f32 v[146:147], v[146:147], v[148:149]
	s_nop 0
	v_cvt_pk_bf16_f32 v150, v146, v147
	s_nop 0
	ds_write_b16 v172, v150 offset:0
	ds_write_b16_d16_hi v172, v150 offset:128
	s_and_saveexec_b64 s[20:21], vcc
	ds_write_b64 v163, v[152:153] offset:4096
	s_mov_b64 exec, s[20:21]
	s_waitcnt vmcnt(22)
	ds_write_b64 v28, v[52:53] offset:5120
	ds_write_b32 v30, v54 offset:2080
	s_waitcnt lgkmcnt(0)
	s_barrier
; DI bf16_t f2bf(float x) { return (bf16_t)(pk2(x, 0.f) & 0xffffu); }
;     ...
;         for (int n = 0; n < 64; ++n) {
;             const int buf = n & 1;
;             f32x4 a4[4]; bf16x8 vfr[2][2];
; #pragma unroll
;             for (int q = 0; q < 4; ++q) a4[q] = a4n[q];
;             const unsigned kraw = krawn;
; #pragma unroll
;             for (int e = 0; e < 2; ++e)
; #pragma unroll
;                 for (int ks = 0; ks < 2; ++ks) vfr[e][ks] = vfrn[e][ks];
;             if (n + 1 < 64) ldchunk(n + 1);
;             float cum[2];
; #pragma unroll
;             for (int e = 0; e < 2; ++e) {
;                 float z = bb[e];
; #pragma unroll
;                 for (int q = 0; q < 4; ++q) { z += a4[q].x * wa[e][4 * q] + a4[q].y * wa[e][4 * q + 1] + a4[q].z * wa[e][4 * q + 2] + a4[q].w * wa[e][4 * q + 3]; }
;                 cum[e] = (fminf(z, 0.f) - __logf(1.f + __expf(-fabsf(z)))) * (1.f / 16.f);
;             }
; #pragma unroll
;             for (int o = 1; o < 64; o <<= 1) {
;                 const float t0 = __shfl_up(cum[0], o), t1 = __shfl_up(cum[1], o);
;                 if (l >= o) { cum[0] += t0; cum[1] += t1; }
;             }
;             const float tot0 = __shfl(cum[0], 63), tot1 = __shfl(cum[1], 63);
;             kdl[(buf * 16 + 2 * w) * 64 + l] = f2bf(bf2f(kraw & 0xffffu) * __expf(tot0 - cum[0]));
;             kdl[(buf * 16 + 2 * w + 1) * 64 + l] = f2bf(bf2f(kraw >> 16) * __expf(tot1 - cum[1]));
;             if (l == 0) { decl[buf * 16 + 2 * w] = __expf(tot0); decl[buf * 16 + 2 * w + 1] = __expf(tot1); }
;             __syncthreads();
;             const f32x4 d4 = *(const f32x4*)(decl + buf * 16 + (l >> 4) * 4);
; #pragma unroll
;             for (int e = 0; e < 2; ++e) acc[e] = acc[e] * d4;
; #pragma unroll
;             for (int ks = 0; ks < 2; ++ks) {
;                 const bf16x8 af = *(const bf16x8*)(kdl + (buf * 16 + (l & 15)) * 64 + ks * 32 + (l >> 4) * 8);
; #pragma unroll
;                 for (int e = 0; e < 2; ++e) acc[e] = MFMA16(af, vfr[e][ks], acc[e]);
;             }
;             const int cidx = b * 64 + n;
; #pragma unroll
;             for (int e = 0; e < 2; ++e) {
;                 const int vv = (2 * w + e) * 16 + (l & 15);
;                 *(u32x2*)(ST + (((size_t)(cidx * 4 + hh)) * 256 + vv) * 128 + ksl * 16 + (l >> 4) * 4) = pk4(acc[e].x, acc[e].y, acc[e].z, acc[e].w);
;             }
;         }
	ds_read_b128 v[8:11], v29 offset:5120
	ds_read_b128 v[12:15], v29 offset:5136
	ds_read_b128 v[16:19], v29 offset:5152
	ds_read_b128 v[20:23], v29 offset:5168
	ds_read_b32 v24, v31 offset:2080
	global_load_dwordx2 v[52:53], v230, s[26:27]
	global_load_dword v54, v231, s[58:59]
	s_add_u32 s26, s26, 0x1000
	s_addc_u32 s27, s27, 0
	s_add_u32 s58, s58, 0x10000
	s_addc_u32 s59, s59, 0
	v_xor_b32_e32 v26, s57, v25
	v_add_u32_e32 v59, v26, v232
	v_add_u32_e32 v63, 0x20000, v59
	global_load_dwordx4 v[194:197], v59, s[34:35]
	global_load_dwordx4 v[198:201], v59, s[34:35] offset:64
	global_load_dwordx4 v[202:205], v63, s[34:35]
	global_load_dwordx4 v[206:209], v63, s[34:35] offset:64
	s_add_u32 s57, s57, 0x80
	ds_read_b128 v[154:157], v75 offset:0
	ds_read_b128 v[240:243], v164 offset:4096
	ds_read_b128 v[236:239], v75 offset:64
	s_waitcnt lgkmcnt(3)
	v_pk_fma_f32 v[64:65], v[8:9], v[86:87], v[118:119] op_sel:[0,0,0] op_sel_hi:[0,1,1]
	v_pk_mul_f32 v[66:67], v[16:17], v[102:103] op_sel:[0,0] op_sel_hi:[0,1]
	v_pk_fma_f32 v[64:65], v[8:9], v[88:89], v[64:65] op_sel:[1,0,0] op_sel_hi:[1,1,1]
	v_pk_fma_f32 v[66:67], v[16:17], v[104:105], v[66:67] op_sel:[1,0,0] op_sel_hi:[1,1,1]
	v_pk_fma_f32 v[64:65], v[10:11], v[90:91], v[64:65] op_sel:[0,0,0] op_sel_hi:[0,1,1]
	v_pk_fma_f32 v[66:67], v[18:19], v[106:107], v[66:67] op_sel:[0,0,0] op_sel_hi:[0,1,1]
	v_pk_fma_f32 v[64:65], v[10:11], v[92:93], v[64:65] op_sel:[1,0,0] op_sel_hi:[1,1,1]
	v_pk_fma_f32 v[66:67], v[18:19], v[108:109], v[66:67] op_sel:[1,0,0] op_sel_hi:[1,1,1]
	v_pk_fma_f32 v[64:65], v[12:13], v[94:95], v[64:65] op_sel:[0,0,0] op_sel_hi:[0,1,1]
	v_pk_fma_f32 v[66:67], v[20:21], v[110:111], v[66:67] op_sel:[0,0,0] op_sel_hi:[0,1,1]
	v_pk_fma_f32 v[64:65], v[12:13], v[96:97], v[64:65] op_sel:[1,0,0] op_sel_hi:[1,1,1]
	v_pk_fma_f32 v[66:67], v[20:21], v[112:113], v[66:67] op_sel:[1,0,0] op_sel_hi:[1,1,1]
	v_pk_fma_f32 v[64:65], v[14:15], v[98:99], v[64:65] op_sel:[0,0,0] op_sel_hi:[0,1,1]
	v_pk_fma_f32 v[66:67], v[22:23], v[114:115], v[66:67] op_sel:[0,0,0] op_sel_hi:[0,1,1]
	v_pk_fma_f32 v[64:65], v[14:15], v[100:101], v[64:65] op_sel:[1,0,0] op_sel_hi:[1,1,1]
	v_pk_fma_f32 v[66:67], v[22:23], v[116:117], v[66:67] op_sel:[1,0,0] op_sel_hi:[1,1,1]
	v_lshlrev_b32_e32 v148, 16, v24
	v_pk_add_f32 v[64:65], v[64:65], v[66:67]
	v_and_b32_e32 v149, 0xffff0000, v24
	s_waitcnt lgkmcnt(0)
	v_pk_mul_f32 v[0:1], v[0:1], v[240:241]
	v_pk_mul_f32 v[2:3], v[2:3], v[242:243]
	v_pk_mul_f32 v[4:5], v[4:5], v[240:241]
	v_pk_mul_f32 v[6:7], v[6:7], v[242:243]
	s_waitcnt vmcnt(16)
	s_nop 0
	v_mfma_f32_16x16x32_bf16 v[0:3], v[154:157], v[32:35], v[0:3]
	v_mfma_f32_16x16x32_bf16 v[4:7], v[154:157], v[40:43], v[4:7]
	v_mfma_f32_16x16x32_bf16 v[0:3], v[236:239], v[36:39], v[0:3]
	v_mfma_f32_16x16x32_bf16 v[4:7], v[236:239], v[44:47], v[4:7]
	v_mul_f32_e64 v68, |v64|, v220
	v_mul_f32_e64 v69, |v65|, v220
	v_exp_f32_e32 v68, v68
	v_exp_f32_e32 v69, v69
	v_min_f32_e32 v70, 0, v64
	v_min_f32_e32 v71, 0, v65
	v_pk_add_f32 v[68:69], v[68:69], v[222:223]
	s_nop 0
	v_log_f32_e32 v138, v68
	v_log_f32_e32 v139, v69
	s_nop 0
	v_pk_mul_f32 v[140:141], v[138:139], v[224:225]
	s_nop 0
	v_pk_fma_f32 v[142:143], v[138:139], v[224:225], v[140:141] neg_lo:[0,0,1] neg_hi:[0,0,1]
	s_nop 0
	v_pk_fma_f32 v[142:143], v[138:139], v[226:227], v[142:143]
	s_nop 0
	v_pk_fma_f32 v[142:143], v[138:139], v[224:225], v[142:143]
	s_nop 0
	v_pk_add_f32 v[144:145], v[70:71], v[142:143] neg_lo:[0,1] neg_hi:[0,1]
	s_nop 0
	v_pk_mul_f32 v[144:145], v[144:145], v[214:215]
	v_cvt_pk_bf16_f32 v244, v0, v1
	v_cvt_pk_bf16_f32 v245, v2, v3
	v_cvt_pk_bf16_f32 v246, v4, v5
	v_cvt_pk_bf16_f32 v247, v6, v7
	global_store_dwordx2 v234, v[244:245], s[100:101]
	global_store_dwordx2 v235, v[246:247], s[100:101]
	s_add_u32 s100, s100, 0x40000
	s_addc_u32 s101, s101, 0
	v_add_f32_dpp v144, v144, v144 row_shr:1 row_mask:0xf bank_mask:0xf
	v_add_f32_dpp v145, v145, v145 row_shr:1 row_mask:0xf bank_mask:0xf
	s_nop 0
	v_add_f32_dpp v144, v144, v144 row_shr:2 row_mask:0xf bank_mask:0xf
	v_add_f32_dpp v145, v145, v145 row_shr:2 row_mask:0xf bank_mask:0xf
	s_nop 0
	v_add_f32_dpp v144, v144, v144 row_shr:4 row_mask:0xf bank_mask:0xf
	v_add_f32_dpp v145, v145, v145 row_shr:4 row_mask:0xf bank_mask:0xf
	s_nop 0
	v_add_f32_dpp v144, v144, v144 row_shr:8 row_mask:0xf bank_mask:0xf
	v_add_f32_dpp v145, v145, v145 row_shr:8 row_mask:0xf bank_mask:0xf
	s_nop 0
	v_add_f32_dpp v144, v144, v144 row_bcast:15 row_mask:0xa bank_mask:0xf
	v_add_f32_dpp v145, v145, v145 row_bcast:15 row_mask:0xa bank_mask:0xf
	s_nop 0
	v_add_f32_dpp v144, v144, v144 row_bcast:31 row_mask:0xc bank_mask:0xf
	v_add_f32_dpp v145, v145, v145 row_bcast:31 row_mask:0xc bank_mask:0xf
	s_nop 0
	v_readlane_b32 s98, v144, 63
	v_readlane_b32 s99, v145, 63
	s_nop 1
	v_pk_add_f32 v[146:147], s[98:99], v[144:145] neg_lo:[0,1] neg_hi:[0,1]
	v_mul_f32_e64 v152, s98, v228
	v_mul_f32_e64 v153, s99, v228
	v_pk_mul_f32 v[146:147], v[146:147], v[228:229]
	v_exp_f32_e32 v152, v152
	v_exp_f32_e32 v153, v153
	v_exp_f32_e32 v146, v146
	v_exp_f32_e32 v147, v147
	s_nop 0
	v_pk_mul_f32 v[146:147], v[146:147], v[148:149]
	s_nop 0
	v_cvt_pk_bf16_f32 v150, v146, v147
	s_nop 0
	ds_write_b16 v172, v150 offset:2048
	ds_write_b16_d16_hi v172, v150 offset:2176
	s_and_saveexec_b64 s[20:21], vcc
	ds_write_b64 v163, v[152:153] offset:4160
	s_mov_b64 exec, s[20:21]
	s_waitcnt vmcnt(22)
	ds_write_b64 v28, v[56:57] offset:0
	ds_write_b32 v30, v58 offset:0
	s_waitcnt lgkmcnt(0)
	s_barrier
; DI bf16_t f2bf(float x) { return (bf16_t)(pk2(x, 0.f) & 0xffffu); }
;     ...
;         for (int n = 0; n < 64; ++n) {
;             const int buf = n & 1;
;             f32x4 a4[4]; bf16x8 vfr[2][2];
; #pragma unroll
;             for (int q = 0; q < 4; ++q) a4[q] = a4n[q];
;             const unsigned kraw = krawn;
; #pragma unroll
;             for (int e = 0; e < 2; ++e)
; #pragma unroll
;                 for (int ks = 0; ks < 2; ++ks) vfr[e][ks] = vfrn[e][ks];
;             if (n + 1 < 64) ldchunk(n + 1);
;             float cum[2];
; #pragma unroll
;             for (int e = 0; e < 2; ++e) {
;                 float z = bb[e];
; #pragma unroll
;                 for (int q = 0; q < 4; ++q) { z += a4[q].x * wa[e][4 * q] + a4[q].y * wa[e][4 * q + 1] + a4[q].z * wa[e][4 * q + 2] + a4[q].w * wa[e][4 * q + 3]; }
;                 cum[e] = (fminf(z, 0.f) - __logf(1.f + __expf(-fabsf(z)))) * (1.f / 16.f);
;             }
; #pragma unroll
;             for (int o = 1; o < 64; o <<= 1) {
;                 const float t0 = __shfl_up(cum[0], o), t1 = __shfl_up(cum[1], o);
;                 if (l >= o) { cum[0] += t0; cum[1] += t1; }
;             }
;             const float tot0 = __shfl(cum[0], 63), tot1 = __shfl(cum[1], 63);
;             kdl[(buf * 16 + 2 * w) * 64 + l] = f2bf(bf2f(kraw & 0xffffu) * __expf(tot0 - cum[0]));
;             kdl[(buf * 16 + 2 * w + 1) * 64 + l] = f2bf(bf2f(kraw >> 16) * __expf(tot1 - cum[1]));
;             if (l == 0) { decl[buf * 16 + 2 * w] = __expf(tot0); decl[buf * 16 + 2 * w + 1] = __expf(tot1); }
;             __syncthreads();
;             const f32x4 d4 = *(const f32x4*)(decl + buf * 16 + (l >> 4) * 4);
; #pragma unroll
;             for (int e = 0; e < 2; ++e) acc[e] = acc[e] * d4;
; #pragma unroll
;             for (int ks = 0; ks < 2; ++ks) {
;                 const bf16x8 af = *(const bf16x8*)(kdl + (buf * 16 + (l & 15)) * 64 + ks * 32 + (l >> 4) * 8);
; #pragma unroll
;                 for (int e = 0; e < 2; ++e) acc[e] = MFMA16(af, vfr[e][ks], acc[e]);
;             }
;             const int cidx = b * 64 + n;
; #pragma unroll
;             for (int e = 0; e < 2; ++e) {
;                 const int vv = (2 * w + e) * 16 + (l & 15);
;                 *(u32x2*)(ST + (((size_t)(cidx * 4 + hh)) * 256 + vv) * 128 + ksl * 16 + (l >> 4) * 4) = pk4(acc[e].x, acc[e].y, acc[e].z, acc[e].w);
;             }
;         }
	ds_read_b128 v[8:11], v29 offset:0
	ds_read_b128 v[12:15], v29 offset:16
	ds_read_b128 v[16:19], v29 offset:32
	ds_read_b128 v[20:23], v29 offset:48
	ds_read_b32 v24, v31 offset:0
	global_load_dwordx2 v[56:57], v230, s[26:27]
	global_load_dword v58, v231, s[58:59]
	s_add_u32 s26, s26, 0x1000
	s_addc_u32 s27, s27, 0
	s_add_u32 s58, s58, 0x10000
	s_addc_u32 s59, s59, 0
	v_xor_b32_e32 v26, s57, v25
	v_add_u32_e32 v59, v26, v232
	v_add_u32_e32 v63, 0x20000, v59
	global_load_dwordx4 v[32:35], v59, s[34:35]
	global_load_dwordx4 v[36:39], v59, s[34:35] offset:64
	global_load_dwordx4 v[40:43], v63, s[34:35]
	global_load_dwordx4 v[44:47], v63, s[34:35] offset:64
	s_add_u32 s57, s57, 0x80
	ds_read_b128 v[154:157], v75 offset:2048
	ds_read_b128 v[240:243], v164 offset:4160
	ds_read_b128 v[236:239], v75 offset:2112
	s_waitcnt lgkmcnt(3)
	v_pk_fma_f32 v[64:65], v[8:9], v[86:87], v[118:119] op_sel:[0,0,0] op_sel_hi:[0,1,1]
	v_pk_mul_f32 v[66:67], v[16:17], v[102:103] op_sel:[0,0] op_sel_hi:[0,1]
	v_pk_fma_f32 v[64:65], v[8:9], v[88:89], v[64:65] op_sel:[1,0,0] op_sel_hi:[1,1,1]
	v_pk_fma_f32 v[66:67], v[16:17], v[104:105], v[66:67] op_sel:[1,0,0] op_sel_hi:[1,1,1]
	v_pk_fma_f32 v[64:65], v[10:11], v[90:91], v[64:65] op_sel:[0,0,0] op_sel_hi:[0,1,1]
	v_pk_fma_f32 v[66:67], v[18:19], v[106:107], v[66:67] op_sel:[0,0,0] op_sel_hi:[0,1,1]
	v_pk_fma_f32 v[64:65], v[10:11], v[92:93], v[64:65] op_sel:[1,0,0] op_sel_hi:[1,1,1]
	v_pk_fma_f32 v[66:67], v[18:19], v[108:109], v[66:67] op_sel:[1,0,0] op_sel_hi:[1,1,1]
	v_pk_fma_f32 v[64:65], v[12:13], v[94:95], v[64:65] op_sel:[0,0,0] op_sel_hi:[0,1,1]
	v_pk_fma_f32 v[66:67], v[20:21], v[110:111], v[66:67] op_sel:[0,0,0] op_sel_hi:[0,1,1]
	v_pk_fma_f32 v[64:65], v[12:13], v[96:97], v[64:65] op_sel:[1,0,0] op_sel_hi:[1,1,1]
	v_pk_fma_f32 v[66:67], v[20:21], v[112:113], v[66:67] op_sel:[1,0,0] op_sel_hi:[1,1,1]
	v_pk_fma_f32 v[64:65], v[14:15], v[98:99], v[64:65] op_sel:[0,0,0] op_sel_hi:[0,1,1]
	v_pk_fma_f32 v[66:67], v[22:23], v[114:115], v[66:67] op_sel:[0,0,0] op_sel_hi:[0,1,1]
	v_pk_fma_f32 v[64:65], v[14:15], v[100:101], v[64:65] op_sel:[1,0,0] op_sel_hi:[1,1,1]
	v_pk_fma_f32 v[66:67], v[22:23], v[116:117], v[66:67] op_sel:[1,0,0] op_sel_hi:[1,1,1]
	v_lshlrev_b32_e32 v148, 16, v24
	v_pk_add_f32 v[64:65], v[64:65], v[66:67]
	v_and_b32_e32 v149, 0xffff0000, v24
	s_waitcnt lgkmcnt(0)
	v_pk_mul_f32 v[0:1], v[0:1], v[240:241]
	v_pk_mul_f32 v[2:3], v[2:3], v[242:243]
	v_pk_mul_f32 v[4:5], v[4:5], v[240:241]
	v_pk_mul_f32 v[6:7], v[6:7], v[242:243]
	s_waitcnt vmcnt(14)
	s_nop 0
	v_mfma_f32_16x16x32_bf16 v[0:3], v[154:157], v[178:181], v[0:3]
	v_mfma_f32_16x16x32_bf16 v[4:7], v[154:157], v[186:189], v[4:7]
	v_mfma_f32_16x16x32_bf16 v[0:3], v[236:239], v[182:185], v[0:3]
	v_mfma_f32_16x16x32_bf16 v[4:7], v[236:239], v[190:193], v[4:7]
	v_mul_f32_e64 v68, |v64|, v220
	v_mul_f32_e64 v69, |v65|, v220
	v_exp_f32_e32 v68, v68
	v_exp_f32_e32 v69, v69
	v_min_f32_e32 v70, 0, v64
	v_min_f32_e32 v71, 0, v65
	v_pk_add_f32 v[68:69], v[68:69], v[222:223]
	s_nop 0
	v_log_f32_e32 v138, v68
	v_log_f32_e32 v139, v69
	s_nop 0
	v_pk_mul_f32 v[140:141], v[138:139], v[224:225]
	s_nop 0
	v_pk_fma_f32 v[142:143], v[138:139], v[224:225], v[140:141] neg_lo:[0,0,1] neg_hi:[0,0,1]
	s_nop 0
	v_pk_fma_f32 v[142:143], v[138:139], v[226:227], v[142:143]
	s_nop 0
	v_pk_fma_f32 v[142:143], v[138:139], v[224:225], v[142:143]
	s_nop 0
	v_pk_add_f32 v[144:145], v[70:71], v[142:143] neg_lo:[0,1] neg_hi:[0,1]
	s_nop 0
	v_pk_mul_f32 v[144:145], v[144:145], v[214:215]
	v_cvt_pk_bf16_f32 v244, v0, v1
	v_cvt_pk_bf16_f32 v245, v2, v3
	v_cvt_pk_bf16_f32 v246, v4, v5
	v_cvt_pk_bf16_f32 v247, v6, v7
	global_store_dwordx2 v234, v[244:245], s[100:101]
	global_store_dwordx2 v235, v[246:247], s[100:101]
	s_add_u32 s100, s100, 0x40000
	s_addc_u32 s101, s101, 0
	v_add_f32_dpp v144, v144, v144 row_shr:1 row_mask:0xf bank_mask:0xf
	v_add_f32_dpp v145, v145, v145 row_shr:1 row_mask:0xf bank_mask:0xf
	s_nop 0
	v_add_f32_dpp v144, v144, v144 row_shr:2 row_mask:0xf bank_mask:0xf
	v_add_f32_dpp v145, v145, v145 row_shr:2 row_mask:0xf bank_mask:0xf
	s_nop 0
	v_add_f32_dpp v144, v144, v144 row_shr:4 row_mask:0xf bank_mask:0xf
	v_add_f32_dpp v145, v145, v145 row_shr:4 row_mask:0xf bank_mask:0xf
	s_nop 0
	v_add_f32_dpp v144, v144, v144 row_shr:8 row_mask:0xf bank_mask:0xf
	v_add_f32_dpp v145, v145, v145 row_shr:8 row_mask:0xf bank_mask:0xf
	s_nop 0
	v_add_f32_dpp v144, v144, v144 row_bcast:15 row_mask:0xa bank_mask:0xf
	v_add_f32_dpp v145, v145, v145 row_bcast:15 row_mask:0xa bank_mask:0xf
	s_nop 0
	v_add_f32_dpp v144, v144, v144 row_bcast:31 row_mask:0xc bank_mask:0xf
	v_add_f32_dpp v145, v145, v145 row_bcast:31 row_mask:0xc bank_mask:0xf
	s_nop 0
	v_readlane_b32 s98, v144, 63
	v_readlane_b32 s99, v145, 63
	s_nop 1
	v_pk_add_f32 v[146:147], s[98:99], v[144:145] neg_lo:[0,1] neg_hi:[0,1]
	v_mul_f32_e64 v152, s98, v228
	v_mul_f32_e64 v153, s99, v228
	v_pk_mul_f32 v[146:147], v[146:147], v[228:229]
	v_exp_f32_e32 v152, v152
	v_exp_f32_e32 v153, v153
	v_exp_f32_e32 v146, v146
	v_exp_f32_e32 v147, v147
	s_nop 0
	v_pk_mul_f32 v[146:147], v[146:147], v[148:149]
	s_nop 0
	v_cvt_pk_bf16_f32 v150, v146, v147
	s_nop 0
	ds_write_b16 v172, v150 offset:0
	ds_write_b16_d16_hi v172, v150 offset:128
	s_and_saveexec_b64 s[20:21], vcc
	ds_write_b64 v163, v[152:153] offset:4096
	s_mov_b64 exec, s[20:21]
	s_waitcnt vmcnt(20)
	ds_write_b64 v28, v[48:49] offset:5120
	ds_write_b32 v30, v50 offset:2080
	s_waitcnt lgkmcnt(0)
	s_barrier
; DI bf16_t f2bf(float x) { return (bf16_t)(pk2(x, 0.f) & 0xffffu); }
;     ...
;         for (int n = 0; n < 64; ++n) {
;             const int buf = n & 1;
;             f32x4 a4[4]; bf16x8 vfr[2][2];
; #pragma unroll
;             for (int q = 0; q < 4; ++q) a4[q] = a4n[q];
;             const unsigned kraw = krawn;
; #pragma unroll
;             for (int e = 0; e < 2; ++e)
; #pragma unroll
;                 for (int ks = 0; ks < 2; ++ks) vfr[e][ks] = vfrn[e][ks];
;             if (n + 1 < 64) ldchunk(n + 1);
;             float cum[2];
; #pragma unroll
;             for (int e = 0; e < 2; ++e) {
;                 float z = bb[e];
; #pragma unroll
;                 for (int q = 0; q < 4; ++q) { z += a4[q].x * wa[e][4 * q] + a4[q].y * wa[e][4 * q + 1] + a4[q].z * wa[e][4 * q + 2] + a4[q].w * wa[e][4 * q + 3]; }
;                 cum[e] = (fminf(z, 0.f) - __logf(1.f + __expf(-fabsf(z)))) * (1.f / 16.f);
;             }
; #pragma unroll
;             for (int o = 1; o < 64; o <<= 1) {
;                 const float t0 = __shfl_up(cum[0], o), t1 = __shfl_up(cum[1], o);
;                 if (l >= o) { cum[0] += t0; cum[1] += t1; }
;             }
;             const float tot0 = __shfl(cum[0], 63), tot1 = __shfl(cum[1], 63);
;             kdl[(buf * 16 + 2 * w) * 64 + l] = f2bf(bf2f(kraw & 0xffffu) * __expf(tot0 - cum[0]));
;             kdl[(buf * 16 + 2 * w + 1) * 64 + l] = f2bf(bf2f(kraw >> 16) * __expf(tot1 - cum[1]));
;             if (l == 0) { decl[buf * 16 + 2 * w] = __expf(tot0); decl[buf * 16 + 2 * w + 1] = __expf(tot1); }
;             __syncthreads();
;             const f32x4 d4 = *(const f32x4*)(decl + buf * 16 + (l >> 4) * 4);
; #pragma unroll
;             for (int e = 0; e < 2; ++e) acc[e] = acc[e] * d4;
; #pragma unroll
;             for (int ks = 0; ks < 2; ++ks) {
;                 const bf16x8 af = *(const bf16x8*)(kdl + (buf * 16 + (l & 15)) * 64 + ks * 32 + (l >> 4) * 8);
; #pragma unroll
;                 for (int e = 0; e < 2; ++e) acc[e] = MFMA16(af, vfr[e][ks], acc[e]);
;             }
;             const int cidx = b * 64 + n;
; #pragma unroll
;             for (int e = 0; e < 2; ++e) {
;                 const int vv = (2 * w + e) * 16 + (l & 15);
;                 *(u32x2*)(ST + (((size_t)(cidx * 4 + hh)) * 256 + vv) * 128 + ksl * 16 + (l >> 4) * 4) = pk4(acc[e].x, acc[e].y, acc[e].z, acc[e].w);
;             }
;         }
	ds_read_b128 v[8:11], v29 offset:5120
	ds_read_b128 v[12:15], v29 offset:5136
	ds_read_b128 v[16:19], v29 offset:5152
	ds_read_b128 v[20:23], v29 offset:5168
	ds_read_b32 v24, v31 offset:2080
	global_load_dwordx2 v[48:49], v230, s[26:27]
	global_load_dword v50, v231, s[58:59]
	s_add_u32 s26, s26, 0x1000
	s_addc_u32 s27, s27, 0
	s_add_u32 s58, s58, 0x10000
	s_addc_u32 s59, s59, 0
	v_xor_b32_e32 v26, s57, v25
	v_add_u32_e32 v59, v26, v232
	v_add_u32_e32 v63, 0x20000, v59
	global_load_dwordx4 v[178:181], v59, s[34:35]
	global_load_dwordx4 v[182:185], v59, s[34:35] offset:64
	global_load_dwordx4 v[186:189], v63, s[34:35]
	global_load_dwordx4 v[190:193], v63, s[34:35] offset:64
	s_add_u32 s57, s57, 0x80
	ds_read_b128 v[154:157], v75 offset:0
	ds_read_b128 v[240:243], v164 offset:4096
	ds_read_b128 v[236:239], v75 offset:64
	s_waitcnt lgkmcnt(3)
	v_pk_fma_f32 v[64:65], v[8:9], v[86:87], v[118:119] op_sel:[0,0,0] op_sel_hi:[0,1,1]
	v_pk_mul_f32 v[66:67], v[16:17], v[102:103] op_sel:[0,0] op_sel_hi:[0,1]
	v_pk_fma_f32 v[64:65], v[8:9], v[88:89], v[64:65] op_sel:[1,0,0] op_sel_hi:[1,1,1]
	v_pk_fma_f32 v[66:67], v[16:17], v[104:105], v[66:67] op_sel:[1,0,0] op_sel_hi:[1,1,1]
	v_pk_fma_f32 v[64:65], v[10:11], v[90:91], v[64:65] op_sel:[0,0,0] op_sel_hi:[0,1,1]
	v_pk_fma_f32 v[66:67], v[18:19], v[106:107], v[66:67] op_sel:[0,0,0] op_sel_hi:[0,1,1]
	v_pk_fma_f32 v[64:65], v[10:11], v[92:93], v[64:65] op_sel:[1,0,0] op_sel_hi:[1,1,1]
	v_pk_fma_f32 v[66:67], v[18:19], v[108:109], v[66:67] op_sel:[1,0,0] op_sel_hi:[1,1,1]
	v_pk_fma_f32 v[64:65], v[12:13], v[94:95], v[64:65] op_sel:[0,0,0] op_sel_hi:[0,1,1]
	v_pk_fma_f32 v[66:67], v[20:21], v[110:111], v[66:67] op_sel:[0,0,0] op_sel_hi:[0,1,1]
	v_pk_fma_f32 v[64:65], v[12:13], v[96:97], v[64:65] op_sel:[1,0,0] op_sel_hi:[1,1,1]
	v_pk_fma_f32 v[66:67], v[20:21], v[112:113], v[66:67] op_sel:[1,0,0] op_sel_hi:[1,1,1]
	v_pk_fma_f32 v[64:65], v[14:15], v[98:99], v[64:65] op_sel:[0,0,0] op_sel_hi:[0,1,1]
	v_pk_fma_f32 v[66:67], v[22:23], v[114:115], v[66:67] op_sel:[0,0,0] op_sel_hi:[0,1,1]
	v_pk_fma_f32 v[64:65], v[14:15], v[100:101], v[64:65] op_sel:[1,0,0] op_sel_hi:[1,1,1]
	v_pk_fma_f32 v[66:67], v[22:23], v[116:117], v[66:67] op_sel:[1,0,0] op_sel_hi:[1,1,1]
	v_lshlrev_b32_e32 v148, 16, v24
	v_pk_add_f32 v[64:65], v[64:65], v[66:67]
	v_and_b32_e32 v149, 0xffff0000, v24
	s_waitcnt lgkmcnt(0)
	v_pk_mul_f32 v[0:1], v[0:1], v[240:241]
	v_pk_mul_f32 v[2:3], v[2:3], v[242:243]
	v_pk_mul_f32 v[4:5], v[4:5], v[240:241]
	v_pk_mul_f32 v[6:7], v[6:7], v[242:243]
	s_waitcnt vmcnt(16)
	s_nop 0
	v_mfma_f32_16x16x32_bf16 v[0:3], v[154:157], v[194:197], v[0:3]
	v_mfma_f32_16x16x32_bf16 v[4:7], v[154:157], v[202:205], v[4:7]
	v_mfma_f32_16x16x32_bf16 v[0:3], v[236:239], v[198:201], v[0:3]
	v_mfma_f32_16x16x32_bf16 v[4:7], v[236:239], v[206:209], v[4:7]
	v_mul_f32_e64 v68, |v64|, v220
	v_mul_f32_e64 v69, |v65|, v220
	v_exp_f32_e32 v68, v68
	v_exp_f32_e32 v69, v69
	v_min_f32_e32 v70, 0, v64
	v_min_f32_e32 v71, 0, v65
	v_pk_add_f32 v[68:69], v[68:69], v[222:223]
	s_nop 0
	v_log_f32_e32 v138, v68
	v_log_f32_e32 v139, v69
	s_nop 0
	v_pk_mul_f32 v[140:141], v[138:139], v[224:225]
	s_nop 0
	v_pk_fma_f32 v[142:143], v[138:139], v[224:225], v[140:141] neg_lo:[0,0,1] neg_hi:[0,0,1]
	s_nop 0
	v_pk_fma_f32 v[142:143], v[138:139], v[226:227], v[142:143]
	s_nop 0
	v_pk_fma_f32 v[142:143], v[138:139], v[224:225], v[142:143]
	s_nop 0
	v_pk_add_f32 v[144:145], v[70:71], v[142:143] neg_lo:[0,1] neg_hi:[0,1]
	s_nop 0
	v_pk_mul_f32 v[144:145], v[144:145], v[214:215]
	v_cvt_pk_bf16_f32 v244, v0, v1
	v_cvt_pk_bf16_f32 v245, v2, v3
	v_cvt_pk_bf16_f32 v246, v4, v5
	v_cvt_pk_bf16_f32 v247, v6, v7
	global_store_dwordx2 v234, v[244:245], s[100:101]
	global_store_dwordx2 v235, v[246:247], s[100:101]
	s_add_u32 s100, s100, 0x40000
	s_addc_u32 s101, s101, 0
	v_add_f32_dpp v144, v144, v144 row_shr:1 row_mask:0xf bank_mask:0xf
	v_add_f32_dpp v145, v145, v145 row_shr:1 row_mask:0xf bank_mask:0xf
	s_nop 0
	v_add_f32_dpp v144, v144, v144 row_shr:2 row_mask:0xf bank_mask:0xf
	v_add_f32_dpp v145, v145, v145 row_shr:2 row_mask:0xf bank_mask:0xf
	s_nop 0
	v_add_f32_dpp v144, v144, v144 row_shr:4 row_mask:0xf bank_mask:0xf
	v_add_f32_dpp v145, v145, v145 row_shr:4 row_mask:0xf bank_mask:0xf
	s_nop 0
	v_add_f32_dpp v144, v144, v144 row_shr:8 row_mask:0xf bank_mask:0xf
	v_add_f32_dpp v145, v145, v145 row_shr:8 row_mask:0xf bank_mask:0xf
	s_nop 0
	v_add_f32_dpp v144, v144, v144 row_bcast:15 row_mask:0xa bank_mask:0xf
	v_add_f32_dpp v145, v145, v145 row_bcast:15 row_mask:0xa bank_mask:0xf
	s_nop 0
	v_add_f32_dpp v144, v144, v144 row_bcast:31 row_mask:0xc bank_mask:0xf
	v_add_f32_dpp v145, v145, v145 row_bcast:31 row_mask:0xc bank_mask:0xf
	s_nop 0
	v_readlane_b32 s98, v144, 63
	v_readlane_b32 s99, v145, 63
	s_nop 1
	v_pk_add_f32 v[146:147], s[98:99], v[144:145] neg_lo:[0,1] neg_hi:[0,1]
	v_mul_f32_e64 v152, s98, v228
	v_mul_f32_e64 v153, s99, v228
	v_pk_mul_f32 v[146:147], v[146:147], v[228:229]
	v_exp_f32_e32 v152, v152
	v_exp_f32_e32 v153, v153
	v_exp_f32_e32 v146, v146
	v_exp_f32_e32 v147, v147
	s_nop 0
	v_pk_mul_f32 v[146:147], v[146:147], v[148:149]
	s_nop 0
	v_cvt_pk_bf16_f32 v150, v146, v147
	s_nop 0
	ds_write_b16 v172, v150 offset:2048
	ds_write_b16_d16_hi v172, v150 offset:2176
	s_and_saveexec_b64 s[20:21], vcc
	ds_write_b64 v163, v[152:153] offset:4160
	s_mov_b64 exec, s[20:21]
	s_waitcnt vmcnt(22)
	ds_write_b64 v28, v[52:53] offset:0
	ds_write_b32 v30, v54 offset:0
	s_waitcnt lgkmcnt(0)
	s_barrier
; DI bf16_t f2bf(float x) { return (bf16_t)(pk2(x, 0.f) & 0xffffu); }
;     ...
;         for (int n = 0; n < 64; ++n) {
;             const int buf = n & 1;
;             f32x4 a4[4]; bf16x8 vfr[2][2];
; #pragma unroll
;             for (int q = 0; q < 4; ++q) a4[q] = a4n[q];
;             const unsigned kraw = krawn;
; #pragma unroll
;             for (int e = 0; e < 2; ++e)
; #pragma unroll
;                 for (int ks = 0; ks < 2; ++ks) vfr[e][ks] = vfrn[e][ks];
;             if (n + 1 < 64) ldchunk(n + 1);
;             float cum[2];
; #pragma unroll
;             for (int e = 0; e < 2; ++e) {
;                 float z = bb[e];
; #pragma unroll
;                 for (int q = 0; q < 4; ++q) { z += a4[q].x * wa[e][4 * q] + a4[q].y * wa[e][4 * q + 1] + a4[q].z * wa[e][4 * q + 2] + a4[q].w * wa[e][4 * q + 3]; }
;                 cum[e] = (fminf(z, 0.f) - __logf(1.f + __expf(-fabsf(z)))) * (1.f / 16.f);
;             }
; #pragma unroll
;             for (int o = 1; o < 64; o <<= 1) {
;                 const float t0 = __shfl_up(cum[0], o), t1 = __shfl_up(cum[1], o);
;                 if (l >= o) { cum[0] += t0; cum[1] += t1; }
;             }
;             const float tot0 = __shfl(cum[0], 63), tot1 = __shfl(cum[1], 63);
;             kdl[(buf * 16 + 2 * w) * 64 + l] = f2bf(bf2f(kraw & 0xffffu) * __expf(tot0 - cum[0]));
;             kdl[(buf * 16 + 2 * w + 1) * 64 + l] = f2bf(bf2f(kraw >> 16) * __expf(tot1 - cum[1]));
;             if (l == 0) { decl[buf * 16 + 2 * w] = __expf(tot0); decl[buf * 16 + 2 * w + 1] = __expf(tot1); }
;             __syncthreads();
;             const f32x4 d4 = *(const f32x4*)(decl + buf * 16 + (l >> 4) * 4);
; #pragma unroll
;             for (int e = 0; e < 2; ++e) acc[e] = acc[e] * d4;
; #pragma unroll
;             for (int ks = 0; ks < 2; ++ks) {
;                 const bf16x8 af = *(const bf16x8*)(kdl + (buf * 16 + (l & 15)) * 64 + ks * 32 + (l >> 4) * 8);
; #pragma unroll
;                 for (int e = 0; e < 2; ++e) acc[e] = MFMA16(af, vfr[e][ks], acc[e]);
;             }
;             const int cidx = b * 64 + n;
; #pragma unroll
;             for (int e = 0; e < 2; ++e) {
;                 const int vv = (2 * w + e) * 16 + (l & 15);
;                 *(u32x2*)(ST + (((size_t)(cidx * 4 + hh)) * 256 + vv) * 128 + ksl * 16 + (l >> 4) * 4) = pk4(acc[e].x, acc[e].y, acc[e].z, acc[e].w);
;             }
;         }
	ds_read_b128 v[8:11], v29 offset:0
	ds_read_b128 v[12:15], v29 offset:16
	ds_read_b128 v[16:19], v29 offset:32
	ds_read_b128 v[20:23], v29 offset:48
	ds_read_b32 v24, v31 offset:0
	global_load_dwordx2 v[52:53], v230, s[26:27]
	global_load_dword v54, v231, s[58:59]
	s_add_u32 s26, s26, 0x1000
	s_addc_u32 s27, s27, 0
	s_add_u32 s58, s58, 0x10000
	s_addc_u32 s59, s59, 0
	v_xor_b32_e32 v26, s57, v25
	v_add_u32_e32 v59, v26, v232
	v_add_u32_e32 v63, 0x20000, v59
	global_load_dwordx4 v[194:197], v59, s[34:35]
	global_load_dwordx4 v[198:201], v59, s[34:35] offset:64
	global_load_dwordx4 v[202:205], v63, s[34:35]
	global_load_dwordx4 v[206:209], v63, s[34:35] offset:64
	s_add_u32 s57, s57, 0x80
	ds_read_b128 v[154:157], v75 offset:2048
	ds_read_b128 v[240:243], v164 offset:4160
	ds_read_b128 v[236:239], v75 offset:2112
	s_waitcnt lgkmcnt(3)
	v_pk_fma_f32 v[64:65], v[8:9], v[86:87], v[118:119] op_sel:[0,0,0] op_sel_hi:[0,1,1]
	v_pk_mul_f32 v[66:67], v[16:17], v[102:103] op_sel:[0,0] op_sel_hi:[0,1]
	v_pk_fma_f32 v[64:65], v[8:9], v[88:89], v[64:65] op_sel:[1,0,0] op_sel_hi:[1,1,1]
	v_pk_fma_f32 v[66:67], v[16:17], v[104:105], v[66:67] op_sel:[1,0,0] op_sel_hi:[1,1,1]
	v_pk_fma_f32 v[64:65], v[10:11], v[90:91], v[64:65] op_sel:[0,0,0] op_sel_hi:[0,1,1]
	v_pk_fma_f32 v[66:67], v[18:19], v[106:107], v[66:67] op_sel:[0,0,0] op_sel_hi:[0,1,1]
	v_pk_fma_f32 v[64:65], v[10:11], v[92:93], v[64:65] op_sel:[1,0,0] op_sel_hi:[1,1,1]
	v_pk_fma_f32 v[66:67], v[18:19], v[108:109], v[66:67] op_sel:[1,0,0] op_sel_hi:[1,1,1]
	v_pk_fma_f32 v[64:65], v[12:13], v[94:95], v[64:65] op_sel:[0,0,0] op_sel_hi:[0,1,1]
	v_pk_fma_f32 v[66:67], v[20:21], v[110:111], v[66:67] op_sel:[0,0,0] op_sel_hi:[0,1,1]
	v_pk_fma_f32 v[64:65], v[12:13], v[96:97], v[64:65] op_sel:[1,0,0] op_sel_hi:[1,1,1]
	v_pk_fma_f32 v[66:67], v[20:21], v[112:113], v[66:67] op_sel:[1,0,0] op_sel_hi:[1,1,1]
	v_pk_fma_f32 v[64:65], v[14:15], v[98:99], v[64:65] op_sel:[0,0,0] op_sel_hi:[0,1,1]
	v_pk_fma_f32 v[66:67], v[22:23], v[114:115], v[66:67] op_sel:[0,0,0] op_sel_hi:[0,1,1]
	v_pk_fma_f32 v[64:65], v[14:15], v[100:101], v[64:65] op_sel:[1,0,0] op_sel_hi:[1,1,1]
	v_pk_fma_f32 v[66:67], v[22:23], v[116:117], v[66:67] op_sel:[1,0,0] op_sel_hi:[1,1,1]
	v_lshlrev_b32_e32 v148, 16, v24
	v_pk_add_f32 v[64:65], v[64:65], v[66:67]
	v_and_b32_e32 v149, 0xffff0000, v24
	s_waitcnt lgkmcnt(0)
	v_pk_mul_f32 v[0:1], v[0:1], v[240:241]
	v_pk_mul_f32 v[2:3], v[2:3], v[242:243]
	v_pk_mul_f32 v[4:5], v[4:5], v[240:241]
	v_pk_mul_f32 v[6:7], v[6:7], v[242:243]
	s_waitcnt vmcnt(16)
	s_nop 0
	v_mfma_f32_16x16x32_bf16 v[0:3], v[154:157], v[32:35], v[0:3]
	v_mfma_f32_16x16x32_bf16 v[4:7], v[154:157], v[40:43], v[4:7]
	v_mfma_f32_16x16x32_bf16 v[0:3], v[236:239], v[36:39], v[0:3]
	v_mfma_f32_16x16x32_bf16 v[4:7], v[236:239], v[44:47], v[4:7]
	v_mul_f32_e64 v68, |v64|, v220
	v_mul_f32_e64 v69, |v65|, v220
	v_exp_f32_e32 v68, v68
	v_exp_f32_e32 v69, v69
	v_min_f32_e32 v70, 0, v64
	v_min_f32_e32 v71, 0, v65
	v_pk_add_f32 v[68:69], v[68:69], v[222:223]
	s_nop 0
	v_log_f32_e32 v138, v68
	v_log_f32_e32 v139, v69
	s_nop 0
	v_pk_mul_f32 v[140:141], v[138:139], v[224:225]
	s_nop 0
	v_pk_fma_f32 v[142:143], v[138:139], v[224:225], v[140:141] neg_lo:[0,0,1] neg_hi:[0,0,1]
	s_nop 0
	v_pk_fma_f32 v[142:143], v[138:139], v[226:227], v[142:143]
	s_nop 0
	v_pk_fma_f32 v[142:143], v[138:139], v[224:225], v[142:143]
	s_nop 0
	v_pk_add_f32 v[144:145], v[70:71], v[142:143] neg_lo:[0,1] neg_hi:[0,1]
	s_nop 0
	v_pk_mul_f32 v[144:145], v[144:145], v[214:215]
	v_cvt_pk_bf16_f32 v244, v0, v1
	v_cvt_pk_bf16_f32 v245, v2, v3
	v_cvt_pk_bf16_f32 v246, v4, v5
	v_cvt_pk_bf16_f32 v247, v6, v7
	global_store_dwordx2 v234, v[244:245], s[100:101]
	global_store_dwordx2 v235, v[246:247], s[100:101]
	s_add_u32 s100, s100, 0x40000
	s_addc_u32 s101, s101, 0
	v_add_f32_dpp v144, v144, v144 row_shr:1 row_mask:0xf bank_mask:0xf
	v_add_f32_dpp v145, v145, v145 row_shr:1 row_mask:0xf bank_mask:0xf
	s_nop 0
	v_add_f32_dpp v144, v144, v144 row_shr:2 row_mask:0xf bank_mask:0xf
	v_add_f32_dpp v145, v145, v145 row_shr:2 row_mask:0xf bank_mask:0xf
	s_nop 0
	v_add_f32_dpp v144, v144, v144 row_shr:4 row_mask:0xf bank_mask:0xf
	v_add_f32_dpp v145, v145, v145 row_shr:4 row_mask:0xf bank_mask:0xf
	s_nop 0
	v_add_f32_dpp v144, v144, v144 row_shr:8 row_mask:0xf bank_mask:0xf
	v_add_f32_dpp v145, v145, v145 row_shr:8 row_mask:0xf bank_mask:0xf
	s_nop 0
	v_add_f32_dpp v144, v144, v144 row_bcast:15 row_mask:0xa bank_mask:0xf
	v_add_f32_dpp v145, v145, v145 row_bcast:15 row_mask:0xa bank_mask:0xf
	s_nop 0
	v_add_f32_dpp v144, v144, v144 row_bcast:31 row_mask:0xc bank_mask:0xf
	v_add_f32_dpp v145, v145, v145 row_bcast:31 row_mask:0xc bank_mask:0xf
	s_nop 0
	v_readlane_b32 s98, v144, 63
	v_readlane_b32 s99, v145, 63
	s_nop 1
	v_pk_add_f32 v[146:147], s[98:99], v[144:145] neg_lo:[0,1] neg_hi:[0,1]
	v_mul_f32_e64 v152, s98, v228
	v_mul_f32_e64 v153, s99, v228
	v_pk_mul_f32 v[146:147], v[146:147], v[228:229]
	v_exp_f32_e32 v152, v152
	v_exp_f32_e32 v153, v153
	v_exp_f32_e32 v146, v146
	v_exp_f32_e32 v147, v147
	s_nop 0
	v_pk_mul_f32 v[146:147], v[146:147], v[148:149]
	s_nop 0
	v_cvt_pk_bf16_f32 v150, v146, v147
	s_nop 0
	ds_write_b16 v172, v150 offset:0
	ds_write_b16_d16_hi v172, v150 offset:128
	s_and_saveexec_b64 s[20:21], vcc
	ds_write_b64 v163, v[152:153] offset:4096
	s_mov_b64 exec, s[20:21]
	s_waitcnt vmcnt(22)
	ds_write_b64 v28, v[56:57] offset:5120
	ds_write_b32 v30, v58 offset:2080
	s_waitcnt lgkmcnt(0)
	s_barrier
; DI bf16_t f2bf(float x) { return (bf16_t)(pk2(x, 0.f) & 0xffffu); }
;     ...
;         for (int n = 0; n < 64; ++n) {
;             const int buf = n & 1;
;             f32x4 a4[4]; bf16x8 vfr[2][2];
; #pragma unroll
;             for (int q = 0; q < 4; ++q) a4[q] = a4n[q];
;             const unsigned kraw = krawn;
; #pragma unroll
;             for (int e = 0; e < 2; ++e)
; #pragma unroll
;                 for (int ks = 0; ks < 2; ++ks) vfr[e][ks] = vfrn[e][ks];
;             if (n + 1 < 64) ldchunk(n + 1);
;             float cum[2];
; #pragma unroll
;             for (int e = 0; e < 2; ++e) {
;                 float z = bb[e];
; #pragma unroll
;                 for (int q = 0; q < 4; ++q) { z += a4[q].x * wa[e][4 * q] + a4[q].y * wa[e][4 * q + 1] + a4[q].z * wa[e][4 * q + 2] + a4[q].w * wa[e][4 * q + 3]; }
;                 cum[e] = (fminf(z, 0.f) - __logf(1.f + __expf(-fabsf(z)))) * (1.f / 16.f);
;             }
; #pragma unroll
;             for (int o = 1; o < 64; o <<= 1) {
;                 const float t0 = __shfl_up(cum[0], o), t1 = __shfl_up(cum[1], o);
;                 if (l >= o) { cum[0] += t0; cum[1] += t1; }
;             }
;             const float tot0 = __shfl(cum[0], 63), tot1 = __shfl(cum[1], 63);
;             kdl[(buf * 16 + 2 * w) * 64 + l] = f2bf(bf2f(kraw & 0xffffu) * __expf(tot0 - cum[0]));
;             kdl[(buf * 16 + 2 * w + 1) * 64 + l] = f2bf(bf2f(kraw >> 16) * __expf(tot1 - cum[1]));
;             if (l == 0) { decl[buf * 16 + 2 * w] = __expf(tot0); decl[buf * 16 + 2 * w + 1] = __expf(tot1); }
;             __syncthreads();
;             const f32x4 d4 = *(const f32x4*)(decl + buf * 16 + (l >> 4) * 4);
; #pragma unroll
;             for (int e = 0; e < 2; ++e) acc[e] = acc[e] * d4;
; #pragma unroll
;             for (int ks = 0; ks < 2; ++ks) {
;                 const bf16x8 af = *(const bf16x8*)(kdl + (buf * 16 + (l & 15)) * 64 + ks * 32 + (l >> 4) * 8);
; #pragma unroll
;                 for (int e = 0; e < 2; ++e) acc[e] = MFMA16(af, vfr[e][ks], acc[e]);
;             }
;             const int cidx = b * 64 + n;
; #pragma unroll
;             for (int e = 0; e < 2; ++e) {
;                 const int vv = (2 * w + e) * 16 + (l & 15);
;                 *(u32x2*)(ST + (((size_t)(cidx * 4 + hh)) * 256 + vv) * 128 + ksl * 16 + (l >> 4) * 4) = pk4(acc[e].x, acc[e].y, acc[e].z, acc[e].w);
;             }
;         }
	ds_read_b128 v[8:11], v29 offset:5120
	ds_read_b128 v[12:15], v29 offset:5136
	ds_read_b128 v[16:19], v29 offset:5152
	ds_read_b128 v[20:23], v29 offset:5168
	ds_read_b32 v24, v31 offset:2080
	global_load_dwordx2 v[56:57], v230, s[26:27]
	global_load_dword v58, v231, s[58:59]
	s_add_u32 s26, s26, 0x1000
	s_addc_u32 s27, s27, 0
	s_add_u32 s58, s58, 0x10000
	s_addc_u32 s59, s59, 0
	v_xor_b32_e32 v26, s57, v25
	v_add_u32_e32 v59, v26, v232
	v_add_u32_e32 v63, 0x20000, v59
	global_load_dwordx4 v[32:35], v59, s[34:35]
	global_load_dwordx4 v[36:39], v59, s[34:35] offset:64
	global_load_dwordx4 v[40:43], v63, s[34:35]
	global_load_dwordx4 v[44:47], v63, s[34:35] offset:64
	s_add_u32 s57, s57, 0x80
	ds_read_b128 v[154:157], v75 offset:0
	ds_read_b128 v[240:243], v164 offset:4096
	ds_read_b128 v[236:239], v75 offset:64
	s_waitcnt lgkmcnt(3)
	v_pk_fma_f32 v[64:65], v[8:9], v[86:87], v[118:119] op_sel:[0,0,0] op_sel_hi:[0,1,1]
	v_pk_mul_f32 v[66:67], v[16:17], v[102:103] op_sel:[0,0] op_sel_hi:[0,1]
	v_pk_fma_f32 v[64:65], v[8:9], v[88:89], v[64:65] op_sel:[1,0,0] op_sel_hi:[1,1,1]
	v_pk_fma_f32 v[66:67], v[16:17], v[104:105], v[66:67] op_sel:[1,0,0] op_sel_hi:[1,1,1]
	v_pk_fma_f32 v[64:65], v[10:11], v[90:91], v[64:65] op_sel:[0,0,0] op_sel_hi:[0,1,1]
	v_pk_fma_f32 v[66:67], v[18:19], v[106:107], v[66:67] op_sel:[0,0,0] op_sel_hi:[0,1,1]
	v_pk_fma_f32 v[64:65], v[10:11], v[92:93], v[64:65] op_sel:[1,0,0] op_sel_hi:[1,1,1]
	v_pk_fma_f32 v[66:67], v[18:19], v[108:109], v[66:67] op_sel:[1,0,0] op_sel_hi:[1,1,1]
	v_pk_fma_f32 v[64:65], v[12:13], v[94:95], v[64:65] op_sel:[0,0,0] op_sel_hi:[0,1,1]
	v_pk_fma_f32 v[66:67], v[20:21], v[110:111], v[66:67] op_sel:[0,0,0] op_sel_hi:[0,1,1]
	v_pk_fma_f32 v[64:65], v[12:13], v[96:97], v[64:65] op_sel:[1,0,0] op_sel_hi:[1,1,1]
	v_pk_fma_f32 v[66:67], v[20:21], v[112:113], v[66:67] op_sel:[1,0,0] op_sel_hi:[1,1,1]
	v_pk_fma_f32 v[64:65], v[14:15], v[98:99], v[64:65] op_sel:[0,0,0] op_sel_hi:[0,1,1]
	v_pk_fma_f32 v[66:67], v[22:23], v[114:115], v[66:67] op_sel:[0,0,0] op_sel_hi:[0,1,1]
	v_pk_fma_f32 v[64:65], v[14:15], v[100:101], v[64:65] op_sel:[1,0,0] op_sel_hi:[1,1,1]
	v_pk_fma_f32 v[66:67], v[22:23], v[116:117], v[66:67] op_sel:[1,0,0] op_sel_hi:[1,1,1]
	v_lshlrev_b32_e32 v148, 16, v24
	v_pk_add_f32 v[64:65], v[64:65], v[66:67]
	v_and_b32_e32 v149, 0xffff0000, v24
	s_waitcnt lgkmcnt(0)
	v_pk_mul_f32 v[0:1], v[0:1], v[240:241]
	v_pk_mul_f32 v[2:3], v[2:3], v[242:243]
	v_pk_mul_f32 v[4:5], v[4:5], v[240:241]
	v_pk_mul_f32 v[6:7], v[6:7], v[242:243]
	s_waitcnt vmcnt(16)
	s_nop 0
	v_mfma_f32_16x16x32_bf16 v[0:3], v[154:157], v[178:181], v[0:3]
	v_mfma_f32_16x16x32_bf16 v[4:7], v[154:157], v[186:189], v[4:7]
	v_mfma_f32_16x16x32_bf16 v[0:3], v[236:239], v[182:185], v[0:3]
	v_mfma_f32_16x16x32_bf16 v[4:7], v[236:239], v[190:193], v[4:7]
	v_mul_f32_e64 v68, |v64|, v220
	v_mul_f32_e64 v69, |v65|, v220
	v_exp_f32_e32 v68, v68
	v_exp_f32_e32 v69, v69
	v_min_f32_e32 v70, 0, v64
	v_min_f32_e32 v71, 0, v65
	v_pk_add_f32 v[68:69], v[68:69], v[222:223]
	s_nop 0
	v_log_f32_e32 v138, v68
	v_log_f32_e32 v139, v69
	s_nop 0
	v_pk_mul_f32 v[140:141], v[138:139], v[224:225]
	s_nop 0
	v_pk_fma_f32 v[142:143], v[138:139], v[224:225], v[140:141] neg_lo:[0,0,1] neg_hi:[0,0,1]
	s_nop 0
	v_pk_fma_f32 v[142:143], v[138:139], v[226:227], v[142:143]
	s_nop 0
	v_pk_fma_f32 v[142:143], v[138:139], v[224:225], v[142:143]
	s_nop 0
	v_pk_add_f32 v[144:145], v[70:71], v[142:143] neg_lo:[0,1] neg_hi:[0,1]
	s_nop 0
	v_pk_mul_f32 v[144:145], v[144:145], v[214:215]
	v_cvt_pk_bf16_f32 v244, v0, v1
	v_cvt_pk_bf16_f32 v245, v2, v3
	v_cvt_pk_bf16_f32 v246, v4, v5
	v_cvt_pk_bf16_f32 v247, v6, v7
	global_store_dwordx2 v234, v[244:245], s[100:101]
	global_store_dwordx2 v235, v[246:247], s[100:101]
	s_add_u32 s100, s100, 0x40000
	s_addc_u32 s101, s101, 0
	v_add_f32_dpp v144, v144, v144 row_shr:1 row_mask:0xf bank_mask:0xf
	v_add_f32_dpp v145, v145, v145 row_shr:1 row_mask:0xf bank_mask:0xf
	s_nop 0
	v_add_f32_dpp v144, v144, v144 row_shr:2 row_mask:0xf bank_mask:0xf
	v_add_f32_dpp v145, v145, v145 row_shr:2 row_mask:0xf bank_mask:0xf
	s_nop 0
	v_add_f32_dpp v144, v144, v144 row_shr:4 row_mask:0xf bank_mask:0xf
	v_add_f32_dpp v145, v145, v145 row_shr:4 row_mask:0xf bank_mask:0xf
	s_nop 0
	v_add_f32_dpp v144, v144, v144 row_shr:8 row_mask:0xf bank_mask:0xf
	v_add_f32_dpp v145, v145, v145 row_shr:8 row_mask:0xf bank_mask:0xf
	s_nop 0
	v_add_f32_dpp v144, v144, v144 row_bcast:15 row_mask:0xa bank_mask:0xf
	v_add_f32_dpp v145, v145, v145 row_bcast:15 row_mask:0xa bank_mask:0xf
	s_nop 0
	v_add_f32_dpp v144, v144, v144 row_bcast:31 row_mask:0xc bank_mask:0xf
	v_add_f32_dpp v145, v145, v145 row_bcast:31 row_mask:0xc bank_mask:0xf
	s_nop 0
	v_readlane_b32 s98, v144, 63
	v_readlane_b32 s99, v145, 63
	s_nop 1
	v_pk_add_f32 v[146:147], s[98:99], v[144:145] neg_lo:[0,1] neg_hi:[0,1]
	v_mul_f32_e64 v152, s98, v228
	v_mul_f32_e64 v153, s99, v228
	v_pk_mul_f32 v[146:147], v[146:147], v[228:229]
	v_exp_f32_e32 v152, v152
	v_exp_f32_e32 v153, v153
	v_exp_f32_e32 v146, v146
	v_exp_f32_e32 v147, v147
	s_nop 0
	v_pk_mul_f32 v[146:147], v[146:147], v[148:149]
	s_nop 0
	v_cvt_pk_bf16_f32 v150, v146, v147
	s_nop 0
	ds_write_b16 v172, v150 offset:2048
	ds_write_b16_d16_hi v172, v150 offset:2176
	s_and_saveexec_b64 s[20:21], vcc
	ds_write_b64 v163, v[152:153] offset:4160
	s_mov_b64 exec, s[20:21]
	s_waitcnt vmcnt(22)
	ds_write_b64 v28, v[48:49] offset:0
	ds_write_b32 v30, v50 offset:0
	s_waitcnt lgkmcnt(0)
	s_barrier
	ds_read_b128 v[8:11], v29 offset:0
	ds_read_b128 v[12:15], v29 offset:16
	ds_read_b128 v[16:19], v29 offset:32
	ds_read_b128 v[20:23], v29 offset:48
	ds_read_b32 v24, v31 offset:0
	s_mov_b32 s28, 9

;     ...
;     LANE_DECODE
;     const bf16_t* GQ = (const bf16_t*)(P.ws + OFF_GQ); const bf16_t* ST = (const bf16_t*)(P.ws + OFF_ST); const bf16_t* GR = (const bf16_t*)(P.ws + OFF_GR); bf16_t* OG = (bf16_t*)(P.ws + OFF_OG);
;     const float* on = P.gla_o_norm + j * 1024;
;     f32x2* red = (f32x2*)smem;
;     for (int u = vb; u < 2048; u += nb) {
;         const int cidx = u >> 2, hh = u & 3, tok0 = cidx * 64;
;         bf16x8 bfr[8], afr[2][8];
; #pragma unroll
;         for (int ks = 0; ks < 8; ++ks) {
;             bfr[ks] = *(const bf16x8*)(ST + (((size_t)(cidx * 4 + hh)) * 256 + 32 * w + li) * 128 + ks * 16 + h * 8);
.LBB0_494:
	s_andn2_b64 vcc, exec, s[0:1]
	s_cbranch_vccnz .LBB0_569
	v_mov_b32_e32 v0, v249
	v_readlane_b32 s0, v253, 0
	s_cmpk_gt_i32 s0, 0x7ff
	s_cbranch_scc1 .LBB0_502
	s_lshl_b32 s28, s46, 10
	s_lshl_b64 s[8:9], s[28:29], 2
	v_readlane_b32 s18, v255, 16
	v_and_b32_e32 v78, 31, v0
	v_readlane_b32 s19, v255, 17
	s_add_u32 s8, s18, s8
	s_waitcnt lgkmcnt(0)
	v_ashrrev_i32_e32 v1, 1, v0
	s_addc_u32 s9, s19, s9
	v_lshl_add_u32 v79, v78, 3, 16
	v_bfe_u32 v2, v0, 5, 1
	v_and_b32_e32 v3, 0xffffffe0, v1
	v_readlane_b32 s18, v253, 9
	v_and_b32_e32 v0, 0x1fffffc0, v0
	v_ashrrev_i32_e32 v1, 31, v3
	v_lshlrev_b32_e32 v176, 4, v2
	v_readlane_b32 s19, v253, 10
	v_and_b32_e32 v5, 64, v213
	v_lshl_add_u32 v82, v0, 3, v79
	s_ashr_i32 s1, s0, 31
	v_or_b32_e32 v0, v3, v78
	v_lshl_add_u64 v[48:49], s[18:19], 0, v[176:177]
	v_xor_b32_e32 v4, 32, v213
	v_add_u32_e32 v5, 64, v5
	s_lshl_b64 s[18:19], s[0:1], 16
	v_lshrrev_b32_e32 v6, 2, v0
	v_and_b32_e32 v0, 3, v0
	v_lshlrev_b32_e32 v0, 5, v0
	v_lshl_or_b32 v0, v6, 10, v0
	v_cmp_lt_i32_e32 vcc, v4, v5
	v_lshl_add_u64 v[0:1], s[18:19], 0, v[0:1]
	v_readlane_b32 s18, v254, 52
	v_cndmask_b32_e32 v4, v213, v4, vcc
	v_or_b32_e32 v0, v0, v176
	v_readlane_b32 s19, v254, 53
	v_lshl_or_b32 v80, v2, 2, v3
	v_lshlrev_b32_e32 v81, 2, v4
	v_cmp_eq_u32_e32 vcc, 0, v2
	s_lshl_b32 s20, s0, 4
	v_lshl_add_u64 v[50:51], s[18:19], 0, v[0:1]
	s_branch .LBB0_498

; #define MFMA32(a, b, c) __builtin_amdgcn_mfma_f32_32x32x16_bf16((a), (b), (c), 0, 0, 0)
;     ...
;         const int cidx = u >> 2, hh = u & 3, tok0 = cidx * 64;
;         bf16x8 bfr[8], afr[2][8];
; #pragma unroll
;         for (int ks = 0; ks < 8; ++ks) {
;             bfr[ks] = *(const bf16x8*)(ST + (((size_t)(cidx * 4 + hh)) * 256 + 32 * w + li) * 128 + ks * 16 + h * 8);
; #pragma unroll
;             for (int mi = 0; mi < 2; ++mi) afr[mi][ks] = *(const bf16x8*)(GQ + (size_t)(tok0 + mi * 32 + li) * 512 + hh * 128 + ks * 16 + h * 8);
;         }
;         f32x4 gn[4]; u32x2 rr[2][4];
; #pragma unroll
;         for (int g = 0; g < 4; ++g) {
;             const int v0 = hh * 256 + 32 * w + 8 * g + 4 * h;
;             gn[g] = *(const f32x4*)(on + v0);
; #pragma unroll
;             for (int mi = 0; mi < 2; ++mi) rr[mi][g] = *(const u32x2*)(GR + (size_t)(tok0 + mi * 32 + li) * 1024 + v0);
;         }
;         f32x16 acc[2];
; #pragma unroll
;         for (int mi = 0; mi < 2; ++mi)
; #pragma unroll
;             for (int i = 0; i < 16; ++i) acc[mi][i] = 0.f;
; #pragma unroll
;         for (int ks = 0; ks < 8; ++ks)
; #pragma unroll
;             for (int mi = 0; mi < 2; ++mi) acc[mi] = MFMA32(bfr[ks], afr[mi][ks], acc[mi]);
; #pragma unroll
;         for (int mi = 0; mi < 2; ++mi) {
;             float s1 = 0.f, s2 = 0.f;
; #pragma unroll
;             for (int i = 0; i < 16; ++i) { s1 += acc[mi][i]; s2 += acc[mi][i] * acc[mi][i]; }
;             s1 += __shfl_xor(s1, 32); s2 += __shfl_xor(s2, 32);
;             if (h == 0) red[w * 64 + mi * 32 + li] = (f32x2){s1, s2};
;         }
.LBB0_498:
	s_and_b32 s1, s20, 0xffffffc0
	v_or_b32_e32 v76, s1, v78
	s_lshl_b32 s1, s0, 8
	global_load_dwordx4 v[0:3], v[50:51], off offset:-128
	s_and_b32 s28, s1, 0x300
	v_ashrrev_i32_e32 v77, 31, v76
	v_lshl_add_u64 v[8:9], v[48:49], 0, s[28:29]
	v_lshlrev_b64 v[4:5], 10, v[76:77]
	v_lshl_add_u64 v[104:105], v[8:9], 0, v[4:5]
	global_load_dwordx4 v[4:7], v[104:105], off
	v_or_b32_e32 v108, 32, v76
	v_ashrrev_i32_e32 v109, 31, v108
	v_lshlrev_b64 v[10:11], 10, v[108:109]
	v_lshl_add_u64 v[110:111], v[8:9], 0, v[10:11]
	global_load_dwordx4 v[8:11], v[110:111], off
	global_load_dwordx4 v[32:35], v[50:51], off
	global_load_dwordx4 v[36:39], v[104:105], off offset:32
	global_load_dwordx4 v[40:43], v[110:111], off offset:32
	global_load_dwordx4 v[44:47], v[50:51], off offset:128
	global_load_dwordx4 v[52:55], v[104:105], off offset:64
	global_load_dwordx4 v[56:59], v[110:111], off offset:64
	global_load_dwordx4 v[60:63], v[50:51], off offset:256
	global_load_dwordx4 v[64:67], v[104:105], off offset:96
	global_load_dwordx4 v[68:71], v[110:111], off offset:96
	global_load_dwordx4 v[72:75], v[50:51], off offset:384
	v_readlane_b32 s18, v254, 30
	v_readlane_b32 s19, v254, 31
	s_waitcnt vmcnt(11)
	v_mfma_f32_32x32x16_bf16 v[16:31], v[0:3], v[4:7], 0
	s_waitcnt vmcnt(10)
	v_mfma_f32_32x32x16_bf16 v[0:15], v[0:3], v[8:11], 0
	s_waitcnt vmcnt(8)
	v_mfma_f32_32x32x16_bf16 v[16:31], v[32:35], v[36:39], v[16:31]
	global_load_dwordx4 v[36:39], v[104:105], off offset:128
	s_waitcnt vmcnt(8)
	v_mfma_f32_32x32x16_bf16 v[0:15], v[32:35], v[40:43], v[0:15]
	global_load_dwordx4 v[32:35], v[110:111], off offset:128
	global_load_dwordx4 v[84:87], v[50:51], off offset:512
	global_load_dwordx4 v[40:43], v[104:105], off offset:160
	s_waitcnt vmcnt(9)
	v_mfma_f32_32x32x16_bf16 v[16:31], v[44:47], v[52:55], v[16:31]
	global_load_dwordx4 v[52:55], v[110:111], off offset:160
	global_load_dwordx4 v[88:91], v[50:51], off offset:640
	global_load_dwordx4 v[92:95], v[104:105], off offset:192
	global_load_dwordx4 v[96:99], v[110:111], off offset:192
	global_load_dwordx4 v[100:103], v[50:51], off offset:768
	s_nop 0
	global_load_dwordx4 v[104:107], v[104:105], off offset:224
	s_waitcnt vmcnt(14)
	v_mfma_f32_32x32x16_bf16 v[0:15], v[44:47], v[56:59], v[0:15]
	v_lshlrev_b64 v[56:57], 11, v[108:109]
	s_waitcnt vmcnt(12)
	v_mfma_f32_32x32x16_bf16 v[16:31], v[60:63], v[64:67], v[16:31]
	v_add_u32_e32 v64, s28, v80
	v_ashrrev_i32_e32 v65, 31, v64
	v_or_b32_e32 v58, 24, v64
	v_ashrrev_i32_e32 v59, 31, v58
	s_waitcnt vmcnt(11)
	v_mfma_f32_32x32x16_bf16 v[0:15], v[60:63], v[68:71], v[0:15]
	v_lshlrev_b64 v[68:69], 11, v[76:77]
	v_lshl_add_u64 v[60:61], s[18:19], 0, v[68:69]
	s_waitcnt vmcnt(8)
	v_mfma_f32_32x32x16_bf16 v[0:15], v[72:75], v[32:35], v[0:15]
	v_lshl_add_u64 v[32:33], v[64:65], 2, s[8:9]
	v_lshl_add_u64 v[34:35], v[64:65], 1, s[18:19]
	v_lshl_add_u64 v[62:63], v[34:35], 0, v[68:69]
	v_lshl_add_u64 v[66:67], v[34:35], 0, v[56:57]
	v_mfma_f32_32x32x16_bf16 v[16:31], v[72:75], v[36:39], v[16:31]
	v_or_b32_e32 v36, 8, v64
	v_or_b32_e32 v38, 16, v64
	v_ashrrev_i32_e32 v37, 31, v36
	v_ashrrev_i32_e32 v39, 31, v38
	v_lshlrev_b64 v[70:71], 1, v[36:37]
	v_lshlrev_b64 v[74:75], 1, v[38:39]
	v_lshl_add_u64 v[72:73], s[18:19], 0, v[56:57]
	s_waitcnt vmcnt(6)
	v_mfma_f32_32x32x16_bf16 v[16:31], v[84:87], v[40:43], v[16:31]
	global_load_dwordx4 v[44:47], v[32:33], off
	global_load_dwordx4 v[40:43], v[32:33], off offset:32
	global_load_dwordx4 v[36:39], v[32:33], off offset:64
	s_nop 0
	global_load_dwordx4 v[32:35], v[32:33], off offset:96
	v_lshl_add_u64 v[76:77], v[60:61], 0, v[74:75]
	v_lshl_add_u64 v[74:75], v[72:73], 0, v[74:75]
	s_waitcnt vmcnt(9)
	v_mfma_f32_32x32x16_bf16 v[0:15], v[84:87], v[52:55], v[0:15]
	global_load_dwordx4 v[84:87], v[110:111], off offset:224
	v_lshlrev_b64 v[52:53], 1, v[58:59]
	v_lshl_add_u64 v[54:55], v[60:61], 0, v[70:71]
	v_lshl_add_u64 v[58:59], v[72:73], 0, v[70:71]
	s_waitcnt vmcnt(8)
	v_mfma_f32_32x32x16_bf16 v[16:31], v[88:91], v[92:95], v[16:31]
	v_lshl_add_u64 v[92:93], v[60:61], 0, v[52:53]
	v_lshl_add_u64 v[52:53], v[72:73], 0, v[52:53]
	global_load_dwordx2 v[72:73], v[62:63], off
	global_load_dwordx2 v[60:61], v[66:67], off
	global_load_dwordx2 v[70:71], v[54:55], off
	s_nop 0
	global_load_dwordx2 v[58:59], v[58:59], off
	s_nop 0
	global_load_dwordx2 v[66:67], v[76:77], off
	global_load_dwordx2 v[54:55], v[74:75], off
	global_load_dwordx2 v[62:63], v[92:93], off
	s_nop 0
	global_load_dwordx2 v[52:53], v[52:53], off
	s_waitcnt vmcnt(13)
	v_mfma_f32_32x32x16_bf16 v[16:31], v[100:103], v[104:107], v[16:31]
	v_mfma_f32_32x32x16_bf16 v[0:15], v[88:91], v[96:99], v[0:15]
	s_nop 10
	v_add_f32_e32 v83, 0, v16
	v_mul_f32_e32 v98, v17, v17
	v_mul_f32_e64 v74, v30, v30
	v_mul_f32_e64 v75, v31, v31
	v_fmac_f32_e32 v98, v16, v16
	v_add_f32_e32 v75, v17, v83
	v_pk_mul_f32 v[96:97], v[18:19], v[18:19]
	v_add_f32_e32 v75, v18, v75
	v_fmac_f32_e32 v98, v18, v18
	v_pk_mul_f32 v[94:95], v[20:21], v[20:21]
	v_add_f32_e32 v75, v19, v75
	v_add_f32_e32 v83, v97, v98
	v_add_f32_e32 v75, v20, v75
	v_add_f32_e32 v83, v94, v83
	v_pk_mul_f32 v[92:93], v[22:23], v[22:23]
	v_add_f32_e32 v75, v21, v75
	v_add_f32_e32 v83, v95, v83
	v_add_f32_e32 v75, v22, v75
	v_add_f32_e32 v83, v92, v83
	v_pk_mul_f32 v[90:91], v[24:25], v[24:25]
	v_add_f32_e32 v75, v23, v75
	v_add_f32_e32 v83, v93, v83
	v_add_f32_e32 v75, v24, v75
	v_add_f32_e32 v83, v90, v83
	v_pk_mul_f32 v[88:89], v[26:27], v[26:27]
	v_add_f32_e32 v75, v25, v75
	v_add_f32_e32 v83, v91, v83
	v_add_f32_e32 v75, v26, v75
	v_add_f32_e32 v83, v88, v83
	v_pk_mul_f32 v[76:77], v[28:29], v[28:29]
	v_add_f32_e32 v75, v27, v75
	v_add_f32_e32 v83, v89, v83
	v_add_f32_e32 v75, v28, v75
	v_add_f32_e32 v76, v76, v83
	v_add_f32_e32 v75, v29, v75
	v_add_f32_e32 v76, v77, v76
	s_waitcnt vmcnt(8)
	v_mfma_f32_32x32x16_bf16 v[0:15], v[100:103], v[84:87], v[0:15]
	v_mul_f32_e32 v99, v31, v31
	v_mov_b32_e32 v96, v31
	v_add_f32_e32 v98, v30, v75
	v_add_f32_e32 v97, v74, v76
	v_add_f32_e64 v74, v96, v98
	v_add_f32_e64 v75, v97, v99
	ds_bpermute_b32 v76, v81, v74
	ds_bpermute_b32 v77, v81, v75
	s_and_saveexec_b64 s[18:19], vcc
	s_cbranch_execz .LBB0_500
	s_waitcnt lgkmcnt(0)
	v_pk_add_f32 v[74:75], v[74:75], v[76:77]
	ds_write_b64 v82, v[74:75]
